# FFN-in GEMM loop: LDS-DMA loads use SGPR base + VGPR offset addressing (16 fewer 64-bit VALU adds per iteration)
# speedup vs baseline: 1.0031x; 1.0031x over previous
; #define PG8_STAGE(bufoff, gbase, voff) do { _Pragma("unroll") for (int _i = 0; _i < 2; ++_i) \
;         __builtin_amdgcn_global_load_lds((const unsigned*)((const char*)(gbase) + (voff)[_i]), (LAS unsigned*)(lds + (bufoff) + ldsw + _i * 8192), 16, 0, 0); } while (0)
; #define PG8_LDA(dst, b, h) do { _Pragma("unroll") for (int m = 0; m < 4; ++m) _Pragma("unroll") for (int k = 0; k < 2; ++k) dst[m][k] = *(const LAS bf16x8*)(lds + PG8_SA(b, h) + aoff + m * 2048 + k * 1024); } while (0)
; #define PG8_LDB(dst, b, h) do { _Pragma("unroll") for (int n = 0; n < 2; ++n) _Pragma("unroll") for (int k = 0; k < 2; ++k) dst[n][k] = *(const LAS bf16x8*)(lds + PG8_SB(b, h) + boff + n * 2048 + k * 1024); } while (0)
; #define PG8_MMA(ai, bj, At, Bt) do { __builtin_amdgcn_s_setprio(1); _Pragma("unroll") for (int m = 0; m < 4; ++m) _Pragma("unroll") for (int n = 0; n < 2; ++n) _Pragma("unroll") for (int k = 0; k < 2; ++k) \
;         acc[ai][bj][m][n] = __builtin_amdgcn_mfma_f32_16x16x32_bf16(Bt[n][k], At[m][k], acc[ai][bj][m][n], 0, 0, 0); __builtin_amdgcn_s_setprio(0); } while (0)
; #define PG8_WAIT_V(n) asm volatile("s_waitcnt vmcnt(" #n ")" ::: "memory")
; #define PG8_WAIT_L(n) asm volatile("s_waitcnt lgkmcnt(" #n ")" ::: "memory")
; #define PG8_BAR __builtin_amdgcn_s_barrier()
; #define PG8_SCHED __builtin_amdgcn_sched_barrier(0)
; template <class Epi>
; __device__ __forceinline__ void gemm_phase(LAS unsigned char* lds, const Gemm g, const StaticOrder& S, const Epi& E, const int tid_in) {
;     ...
;         for (int t = 0; t < nt; t += 2) {
;             const bool last = (t == nt - 2);
;             const char* a1 = cA + (size_t)(t + 1) * kstep;
;             const char* a2 = last ? nA : cA + (size_t)(t + 2) * kstep; const char* b2 = last ? nB : cB + (size_t)(t + 2) * kstep;
;             const char* a3 = a2 + kstep; const char* b3 = b2 + kstep;
;             PG8_LDB(B0, 0, 0); PG8_LDB(B1, 0, 1); PG8_SCHED; PG8_LDA(At, 0, 0); PG8_STAGE(PG8_SA(1, 1), a1 + hstepA, voffA);
;             PG8_WAIT_V(8); PG8_WAIT_L(0); PG8_BAR; PG8_MMA(0, 0, At, B0); PG8_MMA(0, 1, At, B1); PG8_BAR; PG8_SCHED;
;             PG8_LDA(At, 0, 1); PG8_STAGE(PG8_SB(0, 0), b2, voffB); PG8_STAGE(PG8_SB(0, 1), b2 + hstepB, voffB); PG8_STAGE(PG8_SA(0, 0), a2, voffA);
;             PG8_WAIT_V(8); PG8_WAIT_L(0); PG8_BAR; PG8_MMA(1, 0, At, B0); PG8_MMA(1, 1, At, B1); PG8_BAR; PG8_SCHED;
.LBB0_232:
	s_add_u32 s20, s36, 0xfffc0080
	s_addc_u32 s21, s37, -1
	s_add_i32 s57, 0, 0x10000
	s_cmp_eq_u32 s56, 12
	s_cselect_b32 s21, s7, s21
	s_cselect_b32 s20, s17, s20
	s_cselect_b32 s35, s48, s39
	s_cselect_b32 s34, s50, s38
	s_add_i32 s58, 0, 0x14000
	v_add_u32_e32 v44, s57, v163
	v_add_u32_e32 v160, s58, v163
	ds_read_b128 v[32:35], v44
	ds_read_b128 v[36:39], v44 offset:1024
	ds_read_b128 v[40:43], v44 offset:2048
	ds_read_b128 v[44:47], v44 offset:3072
	ds_read_b128 v[168:171], v160
	ds_read_b128 v[172:175], v160 offset:1024
	ds_read_b128 v[176:179], v160 offset:2048
	ds_read_b128 v[180:183], v160 offset:3072
	ds_read_b128 v[184:187], v167
	ds_read_b128 v[188:191], v167 offset:1024
	ds_read_b128 v[192:195], v167 offset:2048
	ds_read_b128 v[196:199], v167 offset:3072
	ds_read_b128 v[200:203], v167 offset:4096
	ds_read_b128 v[204:207], v167 offset:5120
	ds_read_b128 v[208:211], v167 offset:6144
	ds_read_b128 v[212:215], v167 offset:7168
	s_add_i32 m0, s46, 0xc000
	s_nop 0
	global_load_lds_dwordx4 v156, s[36:37]
	s_add_i32 m0, s46, 0xe000
	s_nop 0
	global_load_lds_dwordx4 v158, s[36:37]
	s_waitcnt vmcnt(8)
	s_waitcnt lgkmcnt(0)
	s_barrier
	s_setprio 1
	s_waitcnt lgkmcnt(0)
	v_mfma_f32_16x16x32_bf16 v[142:145], v[32:35], v[184:187], v[142:145]
	v_mfma_f32_16x16x32_bf16 v[138:141], v[40:43], v[184:187], v[138:141]
	v_mfma_f32_16x16x32_bf16 v[124:127], v[32:35], v[192:195], v[124:127]
	v_mfma_f32_16x16x32_bf16 v[120:123], v[40:43], v[192:195], v[120:123]
	v_mfma_f32_16x16x32_bf16 v[108:111], v[32:35], v[200:203], v[108:111]
	v_mfma_f32_16x16x32_bf16 v[104:107], v[40:43], v[200:203], v[104:107]
	v_mfma_f32_16x16x32_bf16 v[92:95], v[32:35], v[208:211], v[92:95]
	v_mfma_f32_16x16x32_bf16 v[88:91], v[40:43], v[208:211], v[88:91]
	v_mfma_f32_16x16x32_bf16 v[142:145], v[36:39], v[188:191], v[142:145]
	v_mfma_f32_16x16x32_bf16 v[138:141], v[44:47], v[188:191], v[138:141]
	v_mfma_f32_16x16x32_bf16 v[124:127], v[36:39], v[196:199], v[124:127]
	v_mfma_f32_16x16x32_bf16 v[120:123], v[44:47], v[196:199], v[120:123]
	v_mfma_f32_16x16x32_bf16 v[108:111], v[36:39], v[204:207], v[108:111]
	v_mfma_f32_16x16x32_bf16 v[104:107], v[44:47], v[204:207], v[104:107]
	v_mfma_f32_16x16x32_bf16 v[92:95], v[36:39], v[212:215], v[92:95]
	v_mfma_f32_16x16x32_bf16 v[88:91], v[44:47], v[212:215], v[88:91]
	s_setprio 0
	s_setprio 1
	v_mfma_f32_16x16x32_bf16 v[134:137], v[168:171], v[184:187], v[134:137]
	v_mfma_f32_16x16x32_bf16 v[130:133], v[176:179], v[184:187], v[130:133]
	v_mfma_f32_16x16x32_bf16 v[116:119], v[168:171], v[192:195], v[116:119]
	v_mfma_f32_16x16x32_bf16 v[112:115], v[176:179], v[192:195], v[112:115]
	v_mfma_f32_16x16x32_bf16 v[100:103], v[168:171], v[200:203], v[100:103]
	v_mfma_f32_16x16x32_bf16 v[96:99], v[176:179], v[200:203], v[96:99]
	v_mfma_f32_16x16x32_bf16 v[84:87], v[168:171], v[208:211], v[84:87]
	v_mfma_f32_16x16x32_bf16 v[80:83], v[176:179], v[208:211], v[80:83]
	v_mfma_f32_16x16x32_bf16 v[134:137], v[172:175], v[188:191], v[134:137]
	v_mfma_f32_16x16x32_bf16 v[130:133], v[180:183], v[188:191], v[130:133]
	v_mfma_f32_16x16x32_bf16 v[116:119], v[172:175], v[196:199], v[116:119]
	v_mfma_f32_16x16x32_bf16 v[112:115], v[180:183], v[196:199], v[112:115]
	v_mfma_f32_16x16x32_bf16 v[100:103], v[172:175], v[204:207], v[100:103]
	v_mfma_f32_16x16x32_bf16 v[96:99], v[180:183], v[204:207], v[96:99]
	v_mfma_f32_16x16x32_bf16 v[84:87], v[172:175], v[212:215], v[84:87]
	v_mfma_f32_16x16x32_bf16 v[80:83], v[180:183], v[212:215], v[80:83]
	s_setprio 0
	s_barrier
	ds_read_b128 v[184:187], v167 offset:16384
	ds_read_b128 v[188:191], v167 offset:17408
	ds_read_b128 v[192:195], v167 offset:18432
	ds_read_b128 v[196:199], v167 offset:19456
	ds_read_b128 v[200:203], v167 offset:20480
	ds_read_b128 v[204:207], v167 offset:21504
	ds_read_b128 v[208:211], v167 offset:22528
	ds_read_b128 v[212:215], v167 offset:23552
	s_add_i32 s57, s57, s45
	s_mov_b32 m0, s57
	s_add_u32 s60, s34, 0x40000
	s_addc_u32 s61, s35, 0
	global_load_lds_dwordx4 v148, s[34:35]
	s_add_i32 m0, s57, 0x2000
	s_add_i32 s57, s58, s45
	global_load_lds_dwordx4 v152, s[34:35]
	s_mov_b32 m0, s57
	s_nop 0
	global_load_lds_dwordx4 v148, s[60:61]
	s_add_i32 m0, s57, 0x2000
	s_nop 0
	global_load_lds_dwordx4 v152, s[60:61]
	s_mov_b32 m0, s46
	s_nop 0
	global_load_lds_dwordx4 v146, s[20:21]
	s_mov_b32 m0, s47
	s_nop 0
	global_load_lds_dwordx4 v150, s[20:21]
	s_waitcnt vmcnt(8)
	s_waitcnt lgkmcnt(0)
	s_barrier
	s_setprio 1
	s_waitcnt lgkmcnt(0)
	v_mfma_f32_16x16x32_bf16 v[76:79], v[32:35], v[184:187], v[76:79]
	v_mfma_f32_16x16x32_bf16 v[72:75], v[40:43], v[184:187], v[72:75]
	v_mfma_f32_16x16x32_bf16 v[60:63], v[32:35], v[192:195], v[60:63]
	v_mfma_f32_16x16x32_bf16 v[56:59], v[40:43], v[192:195], v[56:59]
	v_mfma_f32_16x16x32_bf16 v[28:31], v[32:35], v[200:203], v[28:31]
	v_mfma_f32_16x16x32_bf16 v[24:27], v[40:43], v[200:203], v[24:27]
	v_mfma_f32_16x16x32_bf16 v[12:15], v[32:35], v[208:211], v[12:15]
	v_mfma_f32_16x16x32_bf16 v[8:11], v[40:43], v[208:211], v[8:11]
	v_mfma_f32_16x16x32_bf16 v[76:79], v[36:39], v[188:191], v[76:79]
	v_mfma_f32_16x16x32_bf16 v[72:75], v[44:47], v[188:191], v[72:75]
	v_mfma_f32_16x16x32_bf16 v[60:63], v[36:39], v[196:199], v[60:63]
	v_mfma_f32_16x16x32_bf16 v[56:59], v[44:47], v[196:199], v[56:59]
	v_mfma_f32_16x16x32_bf16 v[28:31], v[36:39], v[204:207], v[28:31]
	v_mfma_f32_16x16x32_bf16 v[24:27], v[44:47], v[204:207], v[24:27]
	v_mfma_f32_16x16x32_bf16 v[12:15], v[36:39], v[212:215], v[12:15]
	v_mfma_f32_16x16x32_bf16 v[8:11], v[44:47], v[212:215], v[8:11]
	s_setprio 0
	s_setprio 1
	v_mfma_f32_16x16x32_bf16 v[20:23], v[168:171], v[200:203], v[20:23]
	v_mfma_f32_16x16x32_bf16 v[16:19], v[176:179], v[200:203], v[16:19]
	v_mfma_f32_16x16x32_bf16 v[4:7], v[168:171], v[208:211], v[4:7]
	v_mfma_f32_16x16x32_bf16 v[0:3], v[176:179], v[208:211], v[0:3]
	v_mfma_f32_16x16x32_bf16 v[32:35], v[168:171], v[184:187], v[68:71]
	v_mfma_f32_16x16x32_bf16 v[36:39], v[176:179], v[184:187], v[64:67]
	v_mfma_f32_16x16x32_bf16 v[40:43], v[168:171], v[192:195], v[52:55]
	v_mfma_f32_16x16x32_bf16 v[44:47], v[176:179], v[192:195], v[48:51]
	v_mfma_f32_16x16x32_bf16 v[20:23], v[172:175], v[204:207], v[20:23]
	v_mfma_f32_16x16x32_bf16 v[16:19], v[180:183], v[204:207], v[16:19]
	v_mfma_f32_16x16x32_bf16 v[4:7], v[172:175], v[212:215], v[4:7]
	v_mfma_f32_16x16x32_bf16 v[0:3], v[180:183], v[212:215], v[0:3]
	v_mfma_f32_16x16x32_bf16 v[32:35], v[172:175], v[188:191], v[32:35]
	v_mfma_f32_16x16x32_bf16 v[36:39], v[180:183], v[188:191], v[36:39]
	v_mfma_f32_16x16x32_bf16 v[40:43], v[172:175], v[196:199], v[40:43]
	v_mfma_f32_16x16x32_bf16 v[44:47], v[180:183], v[196:199], v[44:47]
	s_setprio 0
	s_barrier
; #define PG8_STAGE(bufoff, gbase, voff) do { _Pragma("unroll") for (int _i = 0; _i < 2; ++_i) \
;         __builtin_amdgcn_global_load_lds((const unsigned*)((const char*)(gbase) + (voff)[_i]), (LAS unsigned*)(lds + (bufoff) + ldsw + _i * 8192), 16, 0, 0); } while (0)
; #define PG8_LDA(dst, b, h) do { _Pragma("unroll") for (int m = 0; m < 4; ++m) _Pragma("unroll") for (int k = 0; k < 2; ++k) dst[m][k] = *(const LAS bf16x8*)(lds + PG8_SA(b, h) + aoff + m * 2048 + k * 1024); } while (0)
; #define PG8_LDB(dst, b, h) do { _Pragma("unroll") for (int n = 0; n < 2; ++n) _Pragma("unroll") for (int k = 0; k < 2; ++k) dst[n][k] = *(const LAS bf16x8*)(lds + PG8_SB(b, h) + boff + n * 2048 + k * 1024); } while (0)
; #define PG8_MMA(ai, bj, At, Bt) do { __builtin_amdgcn_s_setprio(1); _Pragma("unroll") for (int m = 0; m < 4; ++m) _Pragma("unroll") for (int n = 0; n < 2; ++n) _Pragma("unroll") for (int k = 0; k < 2; ++k) \
;         acc[ai][bj][m][n] = __builtin_amdgcn_mfma_f32_16x16x32_bf16(Bt[n][k], At[m][k], acc[ai][bj][m][n], 0, 0, 0); __builtin_amdgcn_s_setprio(0); } while (0)
; #define PG8_WAIT_V(n) asm volatile("s_waitcnt vmcnt(" #n ")" ::: "memory")
; #define PG8_WAIT_L(n) asm volatile("s_waitcnt lgkmcnt(" #n ")" ::: "memory")
; #define PG8_BAR __builtin_amdgcn_s_barrier()
; #define PG8_SCHED __builtin_amdgcn_sched_barrier(0)
; template <class Epi>
; __device__ __forceinline__ void gemm_phase(LAS unsigned char* lds, const Gemm g, const StaticOrder& S, const Epi& E, const int tid_in) {
;     ...
;             PG8_LDB(B0, 1, 0); PG8_LDB(B1, 1, 1); PG8_SCHED; PG8_LDA(At, 1, 0); PG8_STAGE(PG8_SA(0, 1), a2 + hstepA, voffA);
;             PG8_WAIT_V(8); PG8_WAIT_L(0); PG8_BAR; PG8_MMA(0, 0, At, B0); PG8_MMA(0, 1, At, B1); PG8_BAR; PG8_SCHED;
;             PG8_LDA(At, 1, 1); PG8_STAGE(PG8_SB(1, 0), b3, voffB); PG8_STAGE(PG8_SB(1, 1), b3 + hstepB, voffB); PG8_STAGE(PG8_SA(1, 0), a3, voffA);
;             PG8_WAIT_V(8); PG8_WAIT_L(0); PG8_BAR; PG8_MMA(1, 0, At, B0); PG8_MMA(1, 1, At, B1); PG8_BAR; PG8_SCHED;
;         }
;         if (wr == 0) PG8_BAR;
	s_add_i32 s57, 0, 0x18000
	s_add_i32 s58, 0, 0x1c000
	v_add_u32_e32 v68, s57, v163
	v_add_u32_e32 v180, s58, v163
	ds_read_b128 v[48:51], v68
	ds_read_b128 v[52:55], v68 offset:1024
	ds_read_b128 v[64:67], v68 offset:2048
	ds_read_b128 v[68:71], v68 offset:3072
	ds_read_b128 v[168:171], v180
	ds_read_b128 v[172:175], v180 offset:1024
	ds_read_b128 v[176:179], v180 offset:2048
	ds_read_b128 v[180:183], v180 offset:3072
	ds_read_b128 v[184:187], v167 offset:32768
	ds_read_b128 v[188:191], v167 offset:33792
	ds_read_b128 v[192:195], v167 offset:34816
	ds_read_b128 v[196:199], v167 offset:35840
	ds_read_b128 v[200:203], v167 offset:36864
	ds_read_b128 v[204:207], v167 offset:37888
	ds_read_b128 v[208:211], v167 offset:38912
	ds_read_b128 v[212:215], v167 offset:39936
	s_add_u32 s20, s20, 0x40000
	s_addc_u32 s21, s21, 0
	s_mov_b32 m0, s71
	s_nop 0
	global_load_lds_dwordx4 v146, s[20:21]
	s_mov_b32 m0, s86
	s_nop 0
	global_load_lds_dwordx4 v150, s[20:21]
	s_waitcnt vmcnt(8)
	s_waitcnt lgkmcnt(0)
	s_barrier
	s_setprio 1
	s_waitcnt lgkmcnt(0)
	v_mfma_f32_16x16x32_bf16 v[142:145], v[48:51], v[184:187], v[142:145]
	v_mfma_f32_16x16x32_bf16 v[138:141], v[64:67], v[184:187], v[138:141]
	v_mfma_f32_16x16x32_bf16 v[124:127], v[48:51], v[192:195], v[124:127]
	v_mfma_f32_16x16x32_bf16 v[120:123], v[64:67], v[192:195], v[120:123]
	v_mfma_f32_16x16x32_bf16 v[108:111], v[48:51], v[200:203], v[108:111]
	v_mfma_f32_16x16x32_bf16 v[104:107], v[64:67], v[200:203], v[104:107]
	v_mfma_f32_16x16x32_bf16 v[92:95], v[48:51], v[208:211], v[92:95]
	v_mfma_f32_16x16x32_bf16 v[88:91], v[64:67], v[208:211], v[88:91]
	v_mfma_f32_16x16x32_bf16 v[142:145], v[52:55], v[188:191], v[142:145]
	v_mfma_f32_16x16x32_bf16 v[138:141], v[68:71], v[188:191], v[138:141]
	v_mfma_f32_16x16x32_bf16 v[124:127], v[52:55], v[196:199], v[124:127]
	v_mfma_f32_16x16x32_bf16 v[120:123], v[68:71], v[196:199], v[120:123]
	v_mfma_f32_16x16x32_bf16 v[108:111], v[52:55], v[204:207], v[108:111]
	v_mfma_f32_16x16x32_bf16 v[104:107], v[68:71], v[204:207], v[104:107]
	v_mfma_f32_16x16x32_bf16 v[92:95], v[52:55], v[212:215], v[92:95]
	v_mfma_f32_16x16x32_bf16 v[88:91], v[68:71], v[212:215], v[88:91]
	s_setprio 0
	s_setprio 1
	v_mfma_f32_16x16x32_bf16 v[134:137], v[168:171], v[184:187], v[134:137]
	v_mfma_f32_16x16x32_bf16 v[130:133], v[176:179], v[184:187], v[130:133]
	v_mfma_f32_16x16x32_bf16 v[116:119], v[168:171], v[192:195], v[116:119]
	v_mfma_f32_16x16x32_bf16 v[112:115], v[176:179], v[192:195], v[112:115]
	v_mfma_f32_16x16x32_bf16 v[100:103], v[168:171], v[200:203], v[100:103]
	v_mfma_f32_16x16x32_bf16 v[96:99], v[176:179], v[200:203], v[96:99]
	v_mfma_f32_16x16x32_bf16 v[84:87], v[168:171], v[208:211], v[84:87]
	v_mfma_f32_16x16x32_bf16 v[80:83], v[176:179], v[208:211], v[80:83]
	v_mfma_f32_16x16x32_bf16 v[134:137], v[172:175], v[188:191], v[134:137]
	v_mfma_f32_16x16x32_bf16 v[130:133], v[180:183], v[188:191], v[130:133]
	v_mfma_f32_16x16x32_bf16 v[116:119], v[172:175], v[196:199], v[116:119]
	v_mfma_f32_16x16x32_bf16 v[112:115], v[180:183], v[196:199], v[112:115]
	v_mfma_f32_16x16x32_bf16 v[100:103], v[172:175], v[204:207], v[100:103]
	v_mfma_f32_16x16x32_bf16 v[96:99], v[180:183], v[204:207], v[96:99]
	v_mfma_f32_16x16x32_bf16 v[84:87], v[172:175], v[212:215], v[84:87]
	v_mfma_f32_16x16x32_bf16 v[80:83], v[180:183], v[212:215], v[80:83]
	s_setprio 0
	s_barrier
	ds_read_b128 v[184:187], v167 offset:49152
	ds_read_b128 v[188:191], v167 offset:50176
	ds_read_b128 v[192:195], v167 offset:51200
	ds_read_b128 v[196:199], v167 offset:52224
	ds_read_b128 v[200:203], v167 offset:53248
	ds_read_b128 v[204:207], v167 offset:54272
	ds_read_b128 v[208:211], v167 offset:55296
	ds_read_b128 v[212:215], v167 offset:56320
	s_add_u32 s98, s20, s54
	s_addc_u32 s99, s21, s55
	s_sub_u32 s98, s98, 0x40000
	s_subb_u32 s99, s99, 0
	s_mov_b32 m0, s88
	s_nop 0
	global_load_lds_dwordx4 v146, s[98:99]
	s_mov_b32 m0, s89
	s_nop 0
	global_load_lds_dwordx4 v150, s[98:99]
	s_add_u32 s98, s34, s54
	s_addc_u32 s99, s35, s55
	s_add_i32 s20, s57, s45
	s_mov_b32 m0, s20
	s_nop 0
	global_load_lds_dwordx4 v148, s[98:99]
	s_add_i32 m0, s20, 0x2000
	s_add_u32 s20, s34, 0x40080
	s_addc_u32 s21, s35, 0
	global_load_lds_dwordx4 v152, s[98:99]
	s_add_i32 s34, s58, s45
	s_mov_b32 m0, s34
	s_nop 0
	global_load_lds_dwordx4 v148, s[20:21]
	s_add_i32 m0, s34, 0x2000
	s_nop 0
	global_load_lds_dwordx4 v152, s[20:21]
	s_waitcnt vmcnt(8)
	s_waitcnt lgkmcnt(0)
	s_barrier
	s_setprio 1
	s_waitcnt lgkmcnt(0)
	v_mfma_f32_16x16x32_bf16 v[76:79], v[48:51], v[184:187], v[76:79]
	v_mfma_f32_16x16x32_bf16 v[72:75], v[64:67], v[184:187], v[72:75]
	v_mfma_f32_16x16x32_bf16 v[60:63], v[48:51], v[192:195], v[60:63]
	v_mfma_f32_16x16x32_bf16 v[56:59], v[64:67], v[192:195], v[56:59]
	v_mfma_f32_16x16x32_bf16 v[28:31], v[48:51], v[200:203], v[28:31]
	v_mfma_f32_16x16x32_bf16 v[24:27], v[64:67], v[200:203], v[24:27]
	v_mfma_f32_16x16x32_bf16 v[12:15], v[48:51], v[208:211], v[12:15]
	v_mfma_f32_16x16x32_bf16 v[8:11], v[64:67], v[208:211], v[8:11]
	v_mfma_f32_16x16x32_bf16 v[76:79], v[52:55], v[188:191], v[76:79]
	v_mfma_f32_16x16x32_bf16 v[72:75], v[68:71], v[188:191], v[72:75]
	v_mfma_f32_16x16x32_bf16 v[60:63], v[52:55], v[196:199], v[60:63]
	v_mfma_f32_16x16x32_bf16 v[56:59], v[68:71], v[196:199], v[56:59]
	v_mfma_f32_16x16x32_bf16 v[28:31], v[52:55], v[204:207], v[28:31]
	v_mfma_f32_16x16x32_bf16 v[24:27], v[68:71], v[204:207], v[24:27]
	v_mfma_f32_16x16x32_bf16 v[12:15], v[52:55], v[212:215], v[12:15]
	v_mfma_f32_16x16x32_bf16 v[8:11], v[68:71], v[212:215], v[8:11]
	s_setprio 0
	s_setprio 1
	v_mfma_f32_16x16x32_bf16 v[32:35], v[168:171], v[184:187], v[32:35]
	v_mfma_f32_16x16x32_bf16 v[68:71], v[172:175], v[188:191], v[32:35]
	v_mfma_f32_16x16x32_bf16 v[32:35], v[176:179], v[184:187], v[36:39]
	v_mfma_f32_16x16x32_bf16 v[64:67], v[180:183], v[188:191], v[32:35]
	v_mfma_f32_16x16x32_bf16 v[32:35], v[168:171], v[192:195], v[40:43]
	v_mfma_f32_16x16x32_bf16 v[52:55], v[172:175], v[196:199], v[32:35]
	v_mfma_f32_16x16x32_bf16 v[32:35], v[176:179], v[192:195], v[44:47]
	v_mfma_f32_16x16x32_bf16 v[20:23], v[168:171], v[200:203], v[20:23]
	v_mfma_f32_16x16x32_bf16 v[16:19], v[176:179], v[200:203], v[16:19]
	v_mfma_f32_16x16x32_bf16 v[4:7], v[168:171], v[208:211], v[4:7]
	v_mfma_f32_16x16x32_bf16 v[0:3], v[176:179], v[208:211], v[0:3]
	v_mfma_f32_16x16x32_bf16 v[48:51], v[180:183], v[196:199], v[32:35]
	v_mfma_f32_16x16x32_bf16 v[20:23], v[172:175], v[204:207], v[20:23]
	v_mfma_f32_16x16x32_bf16 v[16:19], v[180:183], v[204:207], v[16:19]
	v_mfma_f32_16x16x32_bf16 v[4:7], v[172:175], v[212:215], v[4:7]
	v_mfma_f32_16x16x32_bf16 v[0:3], v[180:183], v[212:215], v[0:3]
	s_setprio 0
	s_barrier
	s_add_i32 s56, s56, 2
	s_add_u32 s36, s36, 0x100
	s_addc_u32 s37, s37, 0
	s_add_u32 s38, s38, 0x100
	s_addc_u32 s39, s39, 0
	s_cmp_gt_u32 s56, 13
	s_cbranch_scc0 .LBB0_232
	s_and_b64 vcc, exec, s[28:29]
	s_cbranch_vccz .LBB0_235
	s_barrier
